# ssm_outputs Toeplitz MFMA loop: 4 iterations of LDS fragment reads in flight (counted lgkmcnt) instead of read+wait+MFMA per iteration
# speedup vs baseline: 1.0055x; 1.0055x over previous
; __device__ __forceinline__ void ssm_outputs(const Params& p, int l, char* lds, unsigned* ctr, int* slot) {
;     ...
;       const int nks = tau / 2 + 1;
;       h16x8 A3[4];
; #pragma unroll
;       for (int ks = 0; ks < 4; ++ks)
;         A3[ks] = *(const h16x8*)(W3 + ((size_t)((tau * 16 + ks * 4 + (lane >> 4)) * 16) + (lane & 15)) * 8);
;       for (int i = 0; i < nks; ++i) {
;         int j = tau - (2 * i + hi);
;         h16x8 A = *(const h16x8*)(Kt + (j + 1) * 256 + (lane & 15) * 16 + qh * 8);
;         h16x8 B = *(const h16x8*)(Bu + col * BU_PITCH + (2 * i + hi) * 16 + qh * 8);
;         acc = __builtin_amdgcn_mfma_f32_16x16x32_f16(A, B, acc, 0, 0, 0);
;       }
; #pragma unroll
;       for (int ks = 0; ks < 4; ++ks) {
;         h16x8 B = *(const h16x8*)(Bs + col * BS_PITCH + ks * 32 + (lane >> 4) * 8);
;         acc = __builtin_amdgcn_mfma_f32_16x16x32_f16(A3[ks], B, acc, 0, 0, 0);
;       }
;       const h16* up = Bu + col * BU_PITCH + tau * 16 + p0;
;       size_t tok = ((size_t)b * 128 + ct * 16 + col) * 64 + tau;
;       h16 zz[4];
;       for (int j = 0; j < 4; ++j) zz[j] = (h16)gelu_tanh(dt * acc[j] + dsk[j] * (float)up[j]);
.LBB0_2084:
	v_readfirstlane_b32 s16, v0
	s_and_b32 s17, s16, 3
	s_lshr_b32 s16, s16, 2
	s_cmp_eq_u32 s17, 0
	s_cbranch_scc1 .Lso_q
.Lso_s:
	ds_read_b128 v[70:73], v45
	ds_read_b128 v[74:77], v47
	v_add_u32_e32 v47, 64, v47
	v_add_u32_e32 v45, 0xfffffc00, v45
	s_add_i32 s17, s17, -1
	s_waitcnt lgkmcnt(0)
	v_mfma_f32_16x16x32_f16 v[34:37], v[70:73], v[74:77], v[34:37]
	s_cmp_lg_u32 s17, 0
	s_cbranch_scc1 .Lso_s
.Lso_q:
	s_cmp_eq_u32 s16, 0
	s_cbranch_scc1 .Lso_qdone
.Lso_qloop:
	v_add_u32_e32 v96, 0xfffffc00, v45
	v_add_u32_e32 v97, 0xfffff800, v45
	v_add_u32_e32 v98, 0xfffff400, v45
	ds_read_b128 v[70:73], v45
	ds_read_b128 v[74:77], v47
	ds_read_b128 v[100:103], v96
	ds_read_b128 v[104:107], v47 offset:64
	ds_read_b128 v[108:111], v97
	ds_read_b128 v[112:115], v47 offset:128
	ds_read_b128 v[116:119], v98
	ds_read_b128 v[120:123], v47 offset:192
	v_add_u32_e32 v47, 0x100, v47
	v_add_u32_e32 v45, 0xfffff000, v45
	s_add_i32 s16, s16, -1
	s_waitcnt lgkmcnt(6)
	v_mfma_f32_16x16x32_f16 v[34:37], v[70:73], v[74:77], v[34:37]
	s_waitcnt lgkmcnt(4)
	v_mfma_f32_16x16x32_f16 v[34:37], v[100:103], v[104:107], v[34:37]
	s_waitcnt lgkmcnt(2)
	v_mfma_f32_16x16x32_f16 v[34:37], v[108:111], v[112:115], v[34:37]
	s_waitcnt lgkmcnt(0)
	v_mfma_f32_16x16x32_f16 v[34:37], v[116:119], v[120:123], v[34:37]
	s_cmp_lg_u32 s16, 0
	s_cbranch_scc1 .Lso_qloop
.Lso_qdone:
.LBB0_2086:
	s_or_b64 exec, exec, s[12:13]
	s_waitcnt vmcnt(3) lgkmcnt(3)
	v_mfma_f32_16x16x32_f16 v[18:21], v[18:21], v[2:5], v[34:37]
	v_lshlrev_b32_e32 v0, 5, v58
	s_waitcnt vmcnt(2) lgkmcnt(2)
	v_mfma_f32_16x16x32_f16 v[18:21], v[22:25], v[6:9], v[18:21]
	v_add_u32_e32 v23, v63, v0
	ds_read_u16 v0, v23 offset:33280
	s_waitcnt lgkmcnt(0)
	v_cvt_f32_f16_e32 v25, v0
	s_waitcnt vmcnt(1)
	v_mfma_f32_16x16x32_f16 v[18:21], v[30:33], v[10:13], v[18:21]
	s_waitcnt vmcnt(0)
	v_mfma_f32_16x16x32_f16 v[18:21], v[26:29], v[14:17], v[18:21]
	s_nop 7
	v_mov_b32_e32 v24, v18
	v_pk_mul_f32 v[24:25], v[56:57], v[24:25]
	s_nop 0
	v_add_f32_e32 v0, v24, v25
	v_mul_f32_e32 v18, 0x3d372713, v0
	v_mul_f32_e32 v18, v0, v18
	v_fma_f32 v18, v0, v18, v0
	v_mul_f32_e32 v18, 0x3f4c422a, v18
	v_cmp_nlt_f32_e64 s[12:13], |v18|, s65
	s_and_saveexec_b64 s[16:17], s[12:13]
	s_xor_b64 s[12:13], exec, s[16:17]
	s_cbranch_execz .LBB0_2088
	v_add_f32_e64 v22, |v18|, |v18|
	v_mul_f32_e32 v24, 0x3fb8aa3b, v22
	v_rndne_f32_e32 v25, v24
	v_sub_f32_e32 v26, v24, v25
	v_fma_f32 v24, v22, s66, -v24
	v_fmac_f32_e32 v24, 0x32a5705f, v22
	v_add_f32_e32 v24, v26, v24
	v_cvt_i32_f32_e32 v25, v25
	v_exp_f32_e32 v24, v24
	v_cmp_ngt_f32_e32 vcc, s78, v22
	v_ldexp_f32 v24, v24, v25
	s_nop 0
	v_cndmask_b32_e32 v24, 0, v24, vcc
	v_cmp_nlt_f32_e32 vcc, s79, v22
	s_nop 1
	v_cndmask_b32_e32 v22, v201, v24, vcc
	v_add_f32_e32 v22, 1.0, v22
	v_rcp_f32_e32 v22, v22
	s_nop 0
	v_fma_f32 v22, v22, -2.0, 1.0
